# lru_fix blocked part v2: carry prefix folded cooperatively by the 4 segment-waves (affine maps combined through LDS), row loads issued before the fold and prefetched across the two 8-row batches
# speedup vs baseline: 1.1794x; 1.0051x over previous
; __device__ __forceinline__ void lru_fix_phase(const Params& p, const XcdBarrier& xb) {
;     ...
;   for (int k = 0; k < (blocked ? 1 : 0); k++) {
;     const int li0 = blockIdx.x * 4;
;     const int b = li0 >> 7, s0 = li0 & 127;
;     const float* sg = SEG + (size_t)(b * 128) * 1024 + ch;
;     float carry = 0.f;
; #pragma unroll 8
;     for (int q = 0; q < s0; q++) carry = sg[(size_t)q * 1024] * carry + sg[(size_t)q * 1024 + 512];
.LBB0_1756:
	s_cmpk_lg_i32 s42, 0x100
	s_mov_b32 s0, 0
	s_cbranch_scc1 .LBB0_1776
	v_and_b32_e32 v146, 63, v128
	v_lshrrev_b32_e32 v147, 6, v128
	v_readlane_b32 s7, v254, 0
	v_readfirstlane_b32 s6, v147
	s_nop 3
	s_lshl_b32 s7, s7, 2
	s_lshr_b32 s14, s7, 7
	s_and_b32 s15, s7, 0x7f
	s_and_b32 s16, s6, 1
	s_lshr_b32 s17, s6, 1
	s_add_u32 s18, s15, s17
	s_lshl_b32 s19, s16, 8
	v_lshlrev_b32_e32 v145, 5, v146
	v_lshl_add_u32 v146, v146, 2, s19
	v_lshlrev_b32_e32 v129, 2, v146
	v_lshlrev_b32_e32 v130, 1, v146
	s_lshl_b32 s19, s16, 2
	s_add_u32 s30, s19, s17
	s_lshl_b32 s30, s30, 11
	v_add_u32_e32 v144, s30, v145
	s_lshl_b32 s30, s16, 13
	v_add_u32_e32 v145, s30, v145
	s_add_u32 s7, s7, s17
	s_lshl_b32 s7, s7, 4
	s_lshl_b32 s19, s7, 11
	s_add_u32 s20, s96, 0xd408100
	s_addc_u32 s21, s97, 0
	s_add_u32 s20, s20, s19
	s_addc_u32 s21, s21, 0
	s_add_u32 s22, s96, 0xb308100
	s_addc_u32 s23, s97, 0
	s_add_u32 s22, s22, s19
	s_addc_u32 s23, s23, 0
	s_add_u32 s24, s96, 0x5008500
	s_addc_u32 s25, s97, 0
	s_add_u32 s24, s24, s19
	s_addc_u32 s25, s25, 0
	s_lshl_b32 s19, s7, 12
	s_add_u32 s26, s96, 0x7108900
	s_addc_u32 s27, s97, 0
	s_add_u32 s26, s26, s19
	s_addc_u32 s27, s27, 0
	global_load_dwordx4 v[160:163], v129, s[20:21]
	global_load_dwordx4 v[164:167], v129, s[22:23]
	global_load_dwordx2 v[168:169], v130, s[26:27]
	s_add_u32 s20, s20, 0x800
	s_addc_u32 s21, s21, 0
	s_add_u32 s22, s22, 0x800
	s_addc_u32 s23, s23, 0
	s_add_u32 s26, s26, 0x1000
	s_addc_u32 s27, s27, 0
	global_load_dwordx4 v[170:173], v129, s[20:21]
	global_load_dwordx4 v[174:177], v129, s[22:23]
	global_load_dwordx2 v[178:179], v130, s[26:27]
	s_add_u32 s20, s20, 0x800
	s_addc_u32 s21, s21, 0
	s_add_u32 s22, s22, 0x800
	s_addc_u32 s23, s23, 0
	s_add_u32 s26, s26, 0x1000
	s_addc_u32 s27, s27, 0
	global_load_dwordx4 v[180:183], v129, s[20:21]
	global_load_dwordx4 v[184:187], v129, s[22:23]
	global_load_dwordx2 v[188:189], v130, s[26:27]
	s_add_u32 s20, s20, 0x800
	s_addc_u32 s21, s21, 0
	s_add_u32 s22, s22, 0x800
	s_addc_u32 s23, s23, 0
	s_add_u32 s26, s26, 0x1000
	s_addc_u32 s27, s27, 0
	global_load_dwordx4 v[190:193], v129, s[20:21]
	global_load_dwordx4 v[194:197], v129, s[22:23]
	global_load_dwordx2 v[198:199], v130, s[26:27]
	s_add_u32 s20, s20, 0x800
	s_addc_u32 s21, s21, 0
	s_add_u32 s22, s22, 0x800
	s_addc_u32 s23, s23, 0
	s_add_u32 s26, s26, 0x1000
	s_addc_u32 s27, s27, 0
	global_load_dwordx4 v[200:203], v129, s[20:21]
	global_load_dwordx4 v[204:207], v129, s[22:23]
	global_load_dwordx2 v[208:209], v130, s[26:27]
	s_add_u32 s20, s20, 0x800
	s_addc_u32 s21, s21, 0
	s_add_u32 s22, s22, 0x800
	s_addc_u32 s23, s23, 0
	s_add_u32 s26, s26, 0x1000
	s_addc_u32 s27, s27, 0
	global_load_dwordx4 v[210:213], v129, s[20:21]
	global_load_dwordx4 v[214:217], v129, s[22:23]
	global_load_dwordx2 v[218:219], v130, s[26:27]
	s_add_u32 s20, s20, 0x800
	s_addc_u32 s21, s21, 0
	s_add_u32 s22, s22, 0x800
	s_addc_u32 s23, s23, 0
	s_add_u32 s26, s26, 0x1000
	s_addc_u32 s27, s27, 0
	global_load_dwordx4 v[220:223], v129, s[20:21]
	global_load_dwordx4 v[224:227], v129, s[22:23]
	global_load_dwordx2 v[228:229], v130, s[26:27]
	s_add_u32 s20, s20, 0x800
	s_addc_u32 s21, s21, 0
	s_add_u32 s22, s22, 0x800
	s_addc_u32 s23, s23, 0
	s_add_u32 s26, s26, 0x1000
	s_addc_u32 s27, s27, 0
	global_load_dwordx4 v[230:233], v129, s[20:21]
	global_load_dwordx4 v[234:237], v129, s[22:23]
	global_load_dwordx2 v[238:239], v130, s[26:27]
	s_add_u32 s20, s20, 0x800
	s_addc_u32 s21, s21, 0
	s_add_u32 s22, s22, 0x800
	s_addc_u32 s23, s23, 0
	s_add_u32 s26, s26, 0x1000
	s_addc_u32 s27, s27, 0
	s_lshl_b32 s19, s14, 19
	s_add_u32 s8, s96, 0xf508100
	s_addc_u32 s9, s97, 0
	s_add_u32 s8, s8, s19
	s_addc_u32 s9, s9, 0
	s_lshr_b32 s11, s15, 2
	s_mul_i32 s10, s11, s17
	s_lshl_b32 s12, s10, 12
	s_add_u32 s12, s8, s12
	s_addc_u32 s13, s9, 0
	v_mov_b32_e32 v136, 1.0
	v_mov_b32_e32 v140, 0
	v_mov_b32_e32 v137, 1.0
	v_mov_b32_e32 v141, 0
	v_mov_b32_e32 v138, 1.0
	v_mov_b32_e32 v142, 0
	v_mov_b32_e32 v139, 1.0
	v_mov_b32_e32 v143, 0
.Llf_pre:
	s_cmp_eq_u32 s11, 0
	s_cbranch_scc1 .Llf_pre_done
	global_load_dwordx4 v[0:3], v129, s[12:13]
	global_load_dwordx4 v[4:7], v129, s[12:13] offset:2048
	s_add_u32 s12, s12, 0x1000
	s_addc_u32 s13, s13, 0
	global_load_dwordx4 v[8:11], v129, s[12:13]
	global_load_dwordx4 v[12:15], v129, s[12:13] offset:2048
	s_add_u32 s12, s12, 0x1000
	s_addc_u32 s13, s13, 0
	global_load_dwordx4 v[16:19], v129, s[12:13]
	global_load_dwordx4 v[20:23], v129, s[12:13] offset:2048
	s_add_u32 s12, s12, 0x1000
	s_addc_u32 s13, s13, 0
	global_load_dwordx4 v[24:27], v129, s[12:13]
	global_load_dwordx4 v[28:31], v129, s[12:13] offset:2048
	s_add_u32 s12, s12, 0x1000
	s_addc_u32 s13, s13, 0
	global_load_dwordx4 v[32:35], v129, s[12:13]
	global_load_dwordx4 v[36:39], v129, s[12:13] offset:2048
	s_add_u32 s12, s12, 0x1000
	s_addc_u32 s13, s13, 0
	global_load_dwordx4 v[40:43], v129, s[12:13]
	global_load_dwordx4 v[44:47], v129, s[12:13] offset:2048
	s_add_u32 s12, s12, 0x1000
	s_addc_u32 s13, s13, 0
	global_load_dwordx4 v[48:51], v129, s[12:13]
	global_load_dwordx4 v[52:55], v129, s[12:13] offset:2048
	s_add_u32 s12, s12, 0x1000
	s_addc_u32 s13, s13, 0
	global_load_dwordx4 v[56:59], v129, s[12:13]
	global_load_dwordx4 v[60:63], v129, s[12:13] offset:2048
	s_add_u32 s12, s12, 0x1000
	s_addc_u32 s13, s13, 0
	global_load_dwordx4 v[64:67], v129, s[12:13]
	global_load_dwordx4 v[68:71], v129, s[12:13] offset:2048
	s_add_u32 s12, s12, 0x1000
	s_addc_u32 s13, s13, 0
	global_load_dwordx4 v[72:75], v129, s[12:13]
	global_load_dwordx4 v[76:79], v129, s[12:13] offset:2048
	s_add_u32 s12, s12, 0x1000
	s_addc_u32 s13, s13, 0
	global_load_dwordx4 v[80:83], v129, s[12:13]
	global_load_dwordx4 v[84:87], v129, s[12:13] offset:2048
	s_add_u32 s12, s12, 0x1000
	s_addc_u32 s13, s13, 0
	global_load_dwordx4 v[88:91], v129, s[12:13]
	global_load_dwordx4 v[92:95], v129, s[12:13] offset:2048
	s_add_u32 s12, s12, 0x1000
	s_addc_u32 s13, s13, 0
	global_load_dwordx4 v[96:99], v129, s[12:13]
	global_load_dwordx4 v[100:103], v129, s[12:13] offset:2048
	s_add_u32 s12, s12, 0x1000
	s_addc_u32 s13, s13, 0
	global_load_dwordx4 v[104:107], v129, s[12:13]
	global_load_dwordx4 v[108:111], v129, s[12:13] offset:2048
	s_add_u32 s12, s12, 0x1000
	s_addc_u32 s13, s13, 0
	global_load_dwordx4 v[112:115], v129, s[12:13]
	global_load_dwordx4 v[116:119], v129, s[12:13] offset:2048
	s_add_u32 s12, s12, 0x1000
	s_addc_u32 s13, s13, 0
	global_load_dwordx4 v[120:123], v129, s[12:13]
	global_load_dwordx4 v[124:127], v129, s[12:13] offset:2048
	s_add_u32 s12, s12, 0x1000
	s_addc_u32 s13, s13, 0
	s_waitcnt vmcnt(0)
	v_mul_f32_e32 v136, v136, v0
	v_fma_f32 v140, v140, v0, v4
	v_mul_f32_e32 v137, v137, v1
	v_fma_f32 v141, v141, v1, v5
	v_mul_f32_e32 v138, v138, v2
	v_fma_f32 v142, v142, v2, v6
	v_mul_f32_e32 v139, v139, v3
	v_fma_f32 v143, v143, v3, v7
	s_sub_u32 s11, s11, 1
	s_cmp_eq_u32 s11, 0
	s_cbranch_scc1 .Llf_pre_done
; __device__ __forceinline__ void lru_fix_phase(const Params& p, const XcdBarrier& xb) {
;     ...
;   for (int k = 0; k < (blocked ? 1 : 0); k++) {
;     const int li0 = blockIdx.x * 4;
;     const int b = li0 >> 7, s0 = li0 & 127;
;     const float* sg = SEG + (size_t)(b * 128) * 1024 + ch;
;     float carry = 0.f;
; #pragma unroll 8
;     for (int q = 0; q < s0; q++) carry = sg[(size_t)q * 1024] * carry + sg[(size_t)q * 1024 + 512];
	v_mul_f32_e32 v136, v136, v8
	v_fma_f32 v140, v140, v8, v12
	v_mul_f32_e32 v137, v137, v9
	v_fma_f32 v141, v141, v9, v13
	v_mul_f32_e32 v138, v138, v10
	v_fma_f32 v142, v142, v10, v14
	v_mul_f32_e32 v139, v139, v11
	v_fma_f32 v143, v143, v11, v15
	s_sub_u32 s11, s11, 1
	s_cmp_eq_u32 s11, 0
	s_cbranch_scc1 .Llf_pre_done
	v_mul_f32_e32 v136, v136, v16
	v_fma_f32 v140, v140, v16, v20
	v_mul_f32_e32 v137, v137, v17
	v_fma_f32 v141, v141, v17, v21
	v_mul_f32_e32 v138, v138, v18
	v_fma_f32 v142, v142, v18, v22
	v_mul_f32_e32 v139, v139, v19
	v_fma_f32 v143, v143, v19, v23
	s_sub_u32 s11, s11, 1
	s_cmp_eq_u32 s11, 0
	s_cbranch_scc1 .Llf_pre_done
	v_mul_f32_e32 v136, v136, v24
	v_fma_f32 v140, v140, v24, v28
	v_mul_f32_e32 v137, v137, v25
	v_fma_f32 v141, v141, v25, v29
	v_mul_f32_e32 v138, v138, v26
	v_fma_f32 v142, v142, v26, v30
	v_mul_f32_e32 v139, v139, v27
	v_fma_f32 v143, v143, v27, v31
	s_sub_u32 s11, s11, 1
	s_cmp_eq_u32 s11, 0
	s_cbranch_scc1 .Llf_pre_done
	v_mul_f32_e32 v136, v136, v32
	v_fma_f32 v140, v140, v32, v36
	v_mul_f32_e32 v137, v137, v33
	v_fma_f32 v141, v141, v33, v37
	v_mul_f32_e32 v138, v138, v34
	v_fma_f32 v142, v142, v34, v38
	v_mul_f32_e32 v139, v139, v35
	v_fma_f32 v143, v143, v35, v39
	s_sub_u32 s11, s11, 1
	s_cmp_eq_u32 s11, 0
	s_cbranch_scc1 .Llf_pre_done
	v_mul_f32_e32 v136, v136, v40
	v_fma_f32 v140, v140, v40, v44
	v_mul_f32_e32 v137, v137, v41
	v_fma_f32 v141, v141, v41, v45
	v_mul_f32_e32 v138, v138, v42
	v_fma_f32 v142, v142, v42, v46
	v_mul_f32_e32 v139, v139, v43
	v_fma_f32 v143, v143, v43, v47
	s_sub_u32 s11, s11, 1
	s_cmp_eq_u32 s11, 0
	s_cbranch_scc1 .Llf_pre_done
	v_mul_f32_e32 v136, v136, v48
	v_fma_f32 v140, v140, v48, v52
	v_mul_f32_e32 v137, v137, v49
	v_fma_f32 v141, v141, v49, v53
	v_mul_f32_e32 v138, v138, v50
	v_fma_f32 v142, v142, v50, v54
	v_mul_f32_e32 v139, v139, v51
	v_fma_f32 v143, v143, v51, v55
	s_sub_u32 s11, s11, 1
	s_cmp_eq_u32 s11, 0
	s_cbranch_scc1 .Llf_pre_done
	v_mul_f32_e32 v136, v136, v56
	v_fma_f32 v140, v140, v56, v60
	v_mul_f32_e32 v137, v137, v57
	v_fma_f32 v141, v141, v57, v61
	v_mul_f32_e32 v138, v138, v58
	v_fma_f32 v142, v142, v58, v62
	v_mul_f32_e32 v139, v139, v59
	v_fma_f32 v143, v143, v59, v63
	s_sub_u32 s11, s11, 1
	s_cmp_eq_u32 s11, 0
	s_cbranch_scc1 .Llf_pre_done
	v_mul_f32_e32 v136, v136, v64
	v_fma_f32 v140, v140, v64, v68
	v_mul_f32_e32 v137, v137, v65
	v_fma_f32 v141, v141, v65, v69
	v_mul_f32_e32 v138, v138, v66
	v_fma_f32 v142, v142, v66, v70
	v_mul_f32_e32 v139, v139, v67
	v_fma_f32 v143, v143, v67, v71
	s_sub_u32 s11, s11, 1
	s_cmp_eq_u32 s11, 0
	s_cbranch_scc1 .Llf_pre_done
	v_mul_f32_e32 v136, v136, v72
	v_fma_f32 v140, v140, v72, v76
	v_mul_f32_e32 v137, v137, v73
	v_fma_f32 v141, v141, v73, v77
	v_mul_f32_e32 v138, v138, v74
	v_fma_f32 v142, v142, v74, v78
	v_mul_f32_e32 v139, v139, v75
	v_fma_f32 v143, v143, v75, v79
	s_sub_u32 s11, s11, 1
	s_cmp_eq_u32 s11, 0
	s_cbranch_scc1 .Llf_pre_done
	v_mul_f32_e32 v136, v136, v80
	v_fma_f32 v140, v140, v80, v84
	v_mul_f32_e32 v137, v137, v81
	v_fma_f32 v141, v141, v81, v85
	v_mul_f32_e32 v138, v138, v82
	v_fma_f32 v142, v142, v82, v86
	v_mul_f32_e32 v139, v139, v83
	v_fma_f32 v143, v143, v83, v87
	s_sub_u32 s11, s11, 1
	s_cmp_eq_u32 s11, 0
	s_cbranch_scc1 .Llf_pre_done
	v_mul_f32_e32 v136, v136, v88
	v_fma_f32 v140, v140, v88, v92
	v_mul_f32_e32 v137, v137, v89
	v_fma_f32 v141, v141, v89, v93
	v_mul_f32_e32 v138, v138, v90
	v_fma_f32 v142, v142, v90, v94
	v_mul_f32_e32 v139, v139, v91
	v_fma_f32 v143, v143, v91, v95
	s_sub_u32 s11, s11, 1
	s_cmp_eq_u32 s11, 0
	s_cbranch_scc1 .Llf_pre_done
	v_mul_f32_e32 v136, v136, v96
	v_fma_f32 v140, v140, v96, v100
	v_mul_f32_e32 v137, v137, v97
	v_fma_f32 v141, v141, v97, v101
	v_mul_f32_e32 v138, v138, v98
	v_fma_f32 v142, v142, v98, v102
	v_mul_f32_e32 v139, v139, v99
	v_fma_f32 v143, v143, v99, v103
	s_sub_u32 s11, s11, 1
	s_cmp_eq_u32 s11, 0
	s_cbranch_scc1 .Llf_pre_done
	v_mul_f32_e32 v136, v136, v104
	v_fma_f32 v140, v140, v104, v108
	v_mul_f32_e32 v137, v137, v105
	v_fma_f32 v141, v141, v105, v109
	v_mul_f32_e32 v138, v138, v106
	v_fma_f32 v142, v142, v106, v110
	v_mul_f32_e32 v139, v139, v107
	v_fma_f32 v143, v143, v107, v111
	s_sub_u32 s11, s11, 1
	s_cmp_eq_u32 s11, 0
	s_cbranch_scc1 .Llf_pre_done
	v_mul_f32_e32 v136, v136, v112
	v_fma_f32 v140, v140, v112, v116
	v_mul_f32_e32 v137, v137, v113
	v_fma_f32 v141, v141, v113, v117
	v_mul_f32_e32 v138, v138, v114
	v_fma_f32 v142, v142, v114, v118
	v_mul_f32_e32 v139, v139, v115
	v_fma_f32 v143, v143, v115, v119
	s_sub_u32 s11, s11, 1
	s_cmp_eq_u32 s11, 0
	s_cbranch_scc1 .Llf_pre_done
	v_mul_f32_e32 v136, v136, v120
	v_fma_f32 v140, v140, v120, v124
	v_mul_f32_e32 v137, v137, v121
	v_fma_f32 v141, v141, v121, v125
	v_mul_f32_e32 v138, v138, v122
	v_fma_f32 v142, v142, v122, v126
	v_mul_f32_e32 v139, v139, v123
	v_fma_f32 v143, v143, v123, v127
	s_sub_u32 s11, s11, 1
	s_cmp_eq_u32 s11, 0
	s_cbranch_scc1 .Llf_pre_done
	s_branch .Llf_pre
; __device__ __forceinline__ float bf2f(u16 h) { return __uint_as_float(((unsigned)h) << 16); }
; __device__ __forceinline__ void lru_fix_phase(const Params& p, const XcdBarrier& xb) {
;     ...
;   for (int k = 0; k < (blocked ? 1 : 0); k++) {
;     const int li0 = blockIdx.x * 4;
;     const int b = li0 >> 7, s0 = li0 & 127;
;     const float* sg = SEG + (size_t)(b * 128) * 1024 + ch;
;     float carry = 0.f;
; #pragma unroll 8
;     for (int q = 0; q < s0; q++) carry = sg[(size_t)q * 1024] * carry + sg[(size_t)q * 1024 + 512];
;     for (int u = 0; u < 4; u++) {
;       const int li = li0 + u;
;       const int r0 = li * 16;
; #pragma unroll 8
;       for (int q = 0; q < 16; q++) {
;         const int row = r0 + q;
;         float hv = HL[(size_t)row * 512 + ch] + CA[(size_t)row * 512 + ch] * carry;
;         float gate = geluf_(bf2f(Q[(size_t)row * 2048 + 1024 + ch]));
;         Y[(size_t)row * 1024 + 512 + ch] = f2bf(hv * gate);
;         if ((row & 2047) == 2047) p.out[OUT_PLRU + (size_t)(row >> 11) * 512 + ch] = hv;
;       }
;       carry = sg[(size_t)(s0 + u) * 1024] * carry + sg[(size_t)(s0 + u) * 1024 + 512];
.Llf_pre_done:
	s_lshl_b32 s12, s15, 12
	s_add_u32 s12, s8, s12
	s_addc_u32 s13, s9, 0
	global_load_dwordx4 v[0:3], v129, s[12:13] offset:0
	global_load_dwordx4 v[4:7], v129, s[12:13] offset:2048
	s_add_u32 s12, s12, 0x1000
	s_addc_u32 s13, s13, 0
	global_load_dwordx4 v[8:11], v129, s[12:13] offset:0
	global_load_dwordx4 v[12:15], v129, s[12:13] offset:2048
	s_add_u32 s12, s12, 0x1000
	s_addc_u32 s13, s13, 0
	global_load_dwordx4 v[16:19], v129, s[12:13] offset:0
	global_load_dwordx4 v[20:23], v129, s[12:13] offset:2048
	ds_write_b128 v144, v[136:139]
	ds_write_b128 v144, v[140:143] offset:16
	s_waitcnt lgkmcnt(0)
	s_barrier
	ds_read_b128 v[32:35], v145 offset:0
	ds_read_b128 v[36:39], v145 offset:16
	ds_read_b128 v[40:43], v145 offset:2048
	ds_read_b128 v[44:47], v145 offset:2064
	ds_read_b128 v[48:51], v145 offset:4096
	ds_read_b128 v[52:55], v145 offset:4112
	ds_read_b128 v[56:59], v145 offset:6144
	ds_read_b128 v[60:63], v145 offset:6160
	v_mov_b32_e32 v132, 0
	v_mov_b32_e32 v133, 0
	v_mov_b32_e32 v134, 0
	v_mov_b32_e32 v135, 0
	s_waitcnt lgkmcnt(0)
	v_fma_f32 v132, v132, v32, v36
	v_fma_f32 v133, v133, v33, v37
	v_fma_f32 v134, v134, v34, v38
	v_fma_f32 v135, v135, v35, v39
	v_fma_f32 v132, v132, v40, v44
	v_fma_f32 v133, v133, v41, v45
	v_fma_f32 v134, v134, v42, v46
	v_fma_f32 v135, v135, v43, v47
	v_fma_f32 v132, v132, v48, v52
	v_fma_f32 v133, v133, v49, v53
	v_fma_f32 v134, v134, v50, v54
	v_fma_f32 v135, v135, v51, v55
	v_fma_f32 v132, v132, v56, v60
	v_fma_f32 v133, v133, v57, v61
	v_fma_f32 v134, v134, v58, v62
	v_fma_f32 v135, v135, v59, v63
	s_waitcnt vmcnt(0)
	s_cmp_le_u32 s17, 0
	s_cbranch_scc1 .Llf_own_done
	v_fma_f32 v132, v0, v132, v4
	v_fma_f32 v133, v1, v133, v5
	v_fma_f32 v134, v2, v134, v6
	v_fma_f32 v135, v3, v135, v7
	s_cmp_le_u32 s17, 1
	s_cbranch_scc1 .Llf_own_done
	v_fma_f32 v132, v8, v132, v12
	v_fma_f32 v133, v9, v133, v13
	v_fma_f32 v134, v10, v134, v14
	v_fma_f32 v135, v11, v135, v15
	s_cmp_le_u32 s17, 2
	s_cbranch_scc1 .Llf_own_done
	v_fma_f32 v132, v16, v132, v20
	v_fma_f32 v133, v17, v133, v21
	v_fma_f32 v134, v18, v134, v22
	v_fma_f32 v135, v19, v135, v23
.Llf_own_done:
	s_nop 1
	global_load_dwordx4 v[0:3], v129, s[20:21]
	global_load_dwordx4 v[4:7], v129, s[22:23]
	global_load_dwordx2 v[8:9], v130, s[26:27]
	s_add_u32 s20, s20, 0x800
	s_addc_u32 s21, s21, 0
	s_add_u32 s22, s22, 0x800
	s_addc_u32 s23, s23, 0
	s_add_u32 s26, s26, 0x1000
	s_addc_u32 s27, s27, 0
	global_load_dwordx4 v[10:13], v129, s[20:21]
	global_load_dwordx4 v[14:17], v129, s[22:23]
	global_load_dwordx2 v[18:19], v130, s[26:27]
	s_add_u32 s20, s20, 0x800
	s_addc_u32 s21, s21, 0
	s_add_u32 s22, s22, 0x800
	s_addc_u32 s23, s23, 0
	s_add_u32 s26, s26, 0x1000
	s_addc_u32 s27, s27, 0
	global_load_dwordx4 v[20:23], v129, s[20:21]
	global_load_dwordx4 v[24:27], v129, s[22:23]
	global_load_dwordx2 v[28:29], v130, s[26:27]
	s_add_u32 s20, s20, 0x800
	s_addc_u32 s21, s21, 0
	s_add_u32 s22, s22, 0x800
	s_addc_u32 s23, s23, 0
	s_add_u32 s26, s26, 0x1000
	s_addc_u32 s27, s27, 0
	global_load_dwordx4 v[30:33], v129, s[20:21]
	global_load_dwordx4 v[34:37], v129, s[22:23]
	global_load_dwordx2 v[38:39], v130, s[26:27]
	s_add_u32 s20, s20, 0x800
	s_addc_u32 s21, s21, 0
	s_add_u32 s22, s22, 0x800
	s_addc_u32 s23, s23, 0
	s_add_u32 s26, s26, 0x1000
	s_addc_u32 s27, s27, 0
	global_load_dwordx4 v[40:43], v129, s[20:21]
	global_load_dwordx4 v[44:47], v129, s[22:23]
	global_load_dwordx2 v[48:49], v130, s[26:27]
	s_add_u32 s20, s20, 0x800
	s_addc_u32 s21, s21, 0
	s_add_u32 s22, s22, 0x800
	s_addc_u32 s23, s23, 0
	s_add_u32 s26, s26, 0x1000
	s_addc_u32 s27, s27, 0
	global_load_dwordx4 v[50:53], v129, s[20:21]
	global_load_dwordx4 v[54:57], v129, s[22:23]
	global_load_dwordx2 v[58:59], v130, s[26:27]
	s_add_u32 s20, s20, 0x800
	s_addc_u32 s21, s21, 0
	s_add_u32 s22, s22, 0x800
	s_addc_u32 s23, s23, 0
	s_add_u32 s26, s26, 0x1000
	s_addc_u32 s27, s27, 0
	global_load_dwordx4 v[60:63], v129, s[20:21]
	global_load_dwordx4 v[64:67], v129, s[22:23]
	global_load_dwordx2 v[68:69], v130, s[26:27]
	s_add_u32 s20, s20, 0x800
	s_addc_u32 s21, s21, 0
	s_add_u32 s22, s22, 0x800
	s_addc_u32 s23, s23, 0
	s_add_u32 s26, s26, 0x1000
	s_addc_u32 s27, s27, 0
	global_load_dwordx4 v[70:73], v129, s[20:21]
	global_load_dwordx4 v[74:77], v129, s[22:23]
	global_load_dwordx2 v[78:79], v130, s[26:27]
	s_add_u32 s20, s20, 0x800
	s_addc_u32 s21, s21, 0
	s_add_u32 s22, s22, 0x800
	s_addc_u32 s23, s23, 0
	s_add_u32 s26, s26, 0x1000
	s_addc_u32 s27, s27, 0
	s_waitcnt vmcnt(24)
; __device__ __forceinline__ float bf2f(u16 h) { return __uint_as_float(((unsigned)h) << 16); }
; __device__ __forceinline__ float frcp_(float x) { return __builtin_amdgcn_rcpf(x); }
; __device__ __forceinline__ float tanhf_(float x) {
;   float e = __expf(2.0f * x);
;   return 1.0f - 2.0f * frcp_(1.0f + e);
; }
; __device__ __forceinline__ float geluf_(float x) {
;   float y = 0.7978845608028654f * (x + 0.044715f * x * x * x);
;   return 0.5f * x * (1.0f + tanhf_(y));
; }
; __device__ __forceinline__ void lru_fix_phase(const Params& p, const XcdBarrier& xb) {
;     ...
;       const int li = li0 + u;
;       const int r0 = li * 16;
; #pragma unroll 8
;       for (int q = 0; q < 16; q++) {
;         const int row = r0 + q;
;         float hv = HL[(size_t)row * 512 + ch] + CA[(size_t)row * 512 + ch] * carry;
;         float gate = geluf_(bf2f(Q[(size_t)row * 2048 + 1024 + ch]));
;         Y[(size_t)row * 1024 + 512 + ch] = f2bf(hv * gate);
	v_lshlrev_b32_e32 v146, 16, v168
	v_and_b32_e32 v147, 0xffff0000, v168
	v_lshlrev_b32_e32 v148, 16, v169
	v_and_b32_e32 v149, 0xffff0000, v169
	v_mul_f32_e32 v150, 0x3d372713, v146
	v_mul_f32_e32 v151, 0x3d372713, v147
	v_mul_f32_e32 v152, 0x3d372713, v148
	v_mul_f32_e32 v153, 0x3d372713, v149
	v_mul_f32_e32 v150, v150, v146
	v_mul_f32_e32 v151, v151, v147
	v_mul_f32_e32 v152, v152, v148
	v_mul_f32_e32 v153, v153, v149
	v_fma_f32 v150, v150, v146, v146
	v_fma_f32 v151, v151, v147, v147
	v_fma_f32 v152, v152, v148, v148
	v_fma_f32 v153, v153, v149, v149
	v_mul_f32_e32 v150, 0x3f4c422a, v150
	v_mul_f32_e32 v151, 0x3f4c422a, v151
	v_mul_f32_e32 v152, 0x3f4c422a, v152
	v_mul_f32_e32 v153, 0x3f4c422a, v153
	v_add_f32_e32 v150, v150, v150
	v_add_f32_e32 v151, v151, v151
	v_add_f32_e32 v152, v152, v152
	v_add_f32_e32 v153, v153, v153
	v_mul_f32_e32 v150, 0x3fb8aa3b, v150
	v_mul_f32_e32 v151, 0x3fb8aa3b, v151
	v_mul_f32_e32 v152, 0x3fb8aa3b, v152
	v_mul_f32_e32 v153, 0x3fb8aa3b, v153
	v_exp_f32_e32 v150, v150
	v_exp_f32_e32 v151, v151
	v_exp_f32_e32 v152, v152
	v_exp_f32_e32 v153, v153
	v_mul_f32_e32 v146, 0.5, v146
	v_mul_f32_e32 v147, 0.5, v147
	v_mul_f32_e32 v148, 0.5, v148
	v_mul_f32_e32 v149, 0.5, v149
	v_add_f32_e32 v150, 1.0, v150
	v_add_f32_e32 v151, 1.0, v151
	v_add_f32_e32 v152, 1.0, v152
	v_add_f32_e32 v153, 1.0, v153
	v_rcp_f32_e32 v150, v150
	v_rcp_f32_e32 v151, v151
	v_rcp_f32_e32 v152, v152
	v_rcp_f32_e32 v153, v153
	v_fmac_f32_e32 v160, v132, v164
	v_fmac_f32_e32 v161, v133, v165
	v_fmac_f32_e32 v162, v134, v166
	v_fmac_f32_e32 v163, v135, v167
	v_fma_f32 v150, v150, -2.0, 1.0
	v_fma_f32 v151, v151, -2.0, 1.0
	v_fma_f32 v152, v152, -2.0, 1.0
	v_fma_f32 v153, v153, -2.0, 1.0
	v_add_f32_e32 v150, 1.0, v150
	v_add_f32_e32 v151, 1.0, v151
	v_add_f32_e32 v152, 1.0, v152
	v_add_f32_e32 v153, 1.0, v153
	v_mul_f32_e32 v146, v146, v150
	v_mul_f32_e32 v147, v147, v151
	v_mul_f32_e32 v148, v148, v152
	v_mul_f32_e32 v149, v149, v153
	v_mul_f32_e32 v146, v160, v146
	v_mul_f32_e32 v147, v161, v147
	v_mul_f32_e32 v148, v162, v148
	v_mul_f32_e32 v149, v163, v149
	v_cvt_pk_bf16_f32 v150, v146, v147
	v_cvt_pk_bf16_f32 v151, v148, v149
	global_store_dwordx2 v130, v[150:151], s[24:25]
	s_add_u32 s24, s24, 0x800
	s_addc_u32 s25, s25, 0
	s_nop 0
	v_lshlrev_b32_e32 v146, 16, v178
	v_and_b32_e32 v147, 0xffff0000, v178
	v_lshlrev_b32_e32 v148, 16, v179
	v_and_b32_e32 v149, 0xffff0000, v179
	v_mul_f32_e32 v150, 0x3d372713, v146
	v_mul_f32_e32 v151, 0x3d372713, v147
	v_mul_f32_e32 v152, 0x3d372713, v148
	v_mul_f32_e32 v153, 0x3d372713, v149
	v_mul_f32_e32 v150, v150, v146
	v_mul_f32_e32 v151, v151, v147
	v_mul_f32_e32 v152, v152, v148
	v_mul_f32_e32 v153, v153, v149
	v_fma_f32 v150, v150, v146, v146
	v_fma_f32 v151, v151, v147, v147
	v_fma_f32 v152, v152, v148, v148
	v_fma_f32 v153, v153, v149, v149
	v_mul_f32_e32 v150, 0x3f4c422a, v150
	v_mul_f32_e32 v151, 0x3f4c422a, v151
	v_mul_f32_e32 v152, 0x3f4c422a, v152
	v_mul_f32_e32 v153, 0x3f4c422a, v153
	v_add_f32_e32 v150, v150, v150
	v_add_f32_e32 v151, v151, v151
	v_add_f32_e32 v152, v152, v152
	v_add_f32_e32 v153, v153, v153
	v_mul_f32_e32 v150, 0x3fb8aa3b, v150
	v_mul_f32_e32 v151, 0x3fb8aa3b, v151
	v_mul_f32_e32 v152, 0x3fb8aa3b, v152
	v_mul_f32_e32 v153, 0x3fb8aa3b, v153
	v_exp_f32_e32 v150, v150
	v_exp_f32_e32 v151, v151
	v_exp_f32_e32 v152, v152
	v_exp_f32_e32 v153, v153
	v_mul_f32_e32 v146, 0.5, v146
	v_mul_f32_e32 v147, 0.5, v147
	v_mul_f32_e32 v148, 0.5, v148
	v_mul_f32_e32 v149, 0.5, v149
	v_add_f32_e32 v150, 1.0, v150
	v_add_f32_e32 v151, 1.0, v151
	v_add_f32_e32 v152, 1.0, v152
	v_add_f32_e32 v153, 1.0, v153
	v_rcp_f32_e32 v150, v150
	v_rcp_f32_e32 v151, v151
	v_rcp_f32_e32 v152, v152
	v_rcp_f32_e32 v153, v153
	v_fmac_f32_e32 v170, v132, v174
	v_fmac_f32_e32 v171, v133, v175
	v_fmac_f32_e32 v172, v134, v176
	v_fmac_f32_e32 v173, v135, v177
	v_fma_f32 v150, v150, -2.0, 1.0
	v_fma_f32 v151, v151, -2.0, 1.0
	v_fma_f32 v152, v152, -2.0, 1.0
	v_fma_f32 v153, v153, -2.0, 1.0
	v_add_f32_e32 v150, 1.0, v150
	v_add_f32_e32 v151, 1.0, v151
	v_add_f32_e32 v152, 1.0, v152
	v_add_f32_e32 v153, 1.0, v153
	v_mul_f32_e32 v146, v146, v150
	v_mul_f32_e32 v147, v147, v151
	v_mul_f32_e32 v148, v148, v152
	v_mul_f32_e32 v149, v149, v153
	v_mul_f32_e32 v146, v170, v146
	v_mul_f32_e32 v147, v171, v147
	v_mul_f32_e32 v148, v172, v148
	v_mul_f32_e32 v149, v173, v149
	v_cvt_pk_bf16_f32 v150, v146, v147
	v_cvt_pk_bf16_f32 v151, v148, v149
	global_store_dwordx2 v130, v[150:151], s[24:25]
	s_add_u32 s24, s24, 0x800
	s_addc_u32 s25, s25, 0
	s_nop 0
	v_lshlrev_b32_e32 v146, 16, v188
	v_and_b32_e32 v147, 0xffff0000, v188
	v_lshlrev_b32_e32 v148, 16, v189
	v_and_b32_e32 v149, 0xffff0000, v189
	v_mul_f32_e32 v150, 0x3d372713, v146
	v_mul_f32_e32 v151, 0x3d372713, v147
	v_mul_f32_e32 v152, 0x3d372713, v148
	v_mul_f32_e32 v153, 0x3d372713, v149
	v_mul_f32_e32 v150, v150, v146
	v_mul_f32_e32 v151, v151, v147
	v_mul_f32_e32 v152, v152, v148
	v_mul_f32_e32 v153, v153, v149
	v_fma_f32 v150, v150, v146, v146
	v_fma_f32 v151, v151, v147, v147
	v_fma_f32 v152, v152, v148, v148
	v_fma_f32 v153, v153, v149, v149
	v_mul_f32_e32 v150, 0x3f4c422a, v150
	v_mul_f32_e32 v151, 0x3f4c422a, v151
	v_mul_f32_e32 v152, 0x3f4c422a, v152
	v_mul_f32_e32 v153, 0x3f4c422a, v153
	v_add_f32_e32 v150, v150, v150
	v_add_f32_e32 v151, v151, v151
	v_add_f32_e32 v152, v152, v152
	v_add_f32_e32 v153, v153, v153
	v_mul_f32_e32 v150, 0x3fb8aa3b, v150
	v_mul_f32_e32 v151, 0x3fb8aa3b, v151
	v_mul_f32_e32 v152, 0x3fb8aa3b, v152
	v_mul_f32_e32 v153, 0x3fb8aa3b, v153
	v_exp_f32_e32 v150, v150
	v_exp_f32_e32 v151, v151
	v_exp_f32_e32 v152, v152
	v_exp_f32_e32 v153, v153
; __device__ __forceinline__ float bf2f(u16 h) { return __uint_as_float(((unsigned)h) << 16); }
; __device__ __forceinline__ float frcp_(float x) { return __builtin_amdgcn_rcpf(x); }
; __device__ __forceinline__ float tanhf_(float x) {
;   float e = __expf(2.0f * x);
;   return 1.0f - 2.0f * frcp_(1.0f + e);
; }
; __device__ __forceinline__ float geluf_(float x) {
;   float y = 0.7978845608028654f * (x + 0.044715f * x * x * x);
;   return 0.5f * x * (1.0f + tanhf_(y));
; }
; __device__ __forceinline__ void lru_fix_phase(const Params& p, const XcdBarrier& xb) {
;     ...
;       const int li = li0 + u;
;       const int r0 = li * 16;
; #pragma unroll 8
;       for (int q = 0; q < 16; q++) {
;         const int row = r0 + q;
;         float hv = HL[(size_t)row * 512 + ch] + CA[(size_t)row * 512 + ch] * carry;
;         float gate = geluf_(bf2f(Q[(size_t)row * 2048 + 1024 + ch]));
;         Y[(size_t)row * 1024 + 512 + ch] = f2bf(hv * gate);
	v_mul_f32_e32 v146, 0.5, v146
	v_mul_f32_e32 v147, 0.5, v147
	v_mul_f32_e32 v148, 0.5, v148
	v_mul_f32_e32 v149, 0.5, v149
	v_add_f32_e32 v150, 1.0, v150
	v_add_f32_e32 v151, 1.0, v151
	v_add_f32_e32 v152, 1.0, v152
	v_add_f32_e32 v153, 1.0, v153
	v_rcp_f32_e32 v150, v150
	v_rcp_f32_e32 v151, v151
	v_rcp_f32_e32 v152, v152
	v_rcp_f32_e32 v153, v153
	v_fmac_f32_e32 v180, v132, v184
	v_fmac_f32_e32 v181, v133, v185
	v_fmac_f32_e32 v182, v134, v186
	v_fmac_f32_e32 v183, v135, v187
	v_fma_f32 v150, v150, -2.0, 1.0
	v_fma_f32 v151, v151, -2.0, 1.0
	v_fma_f32 v152, v152, -2.0, 1.0
	v_fma_f32 v153, v153, -2.0, 1.0
	v_add_f32_e32 v150, 1.0, v150
	v_add_f32_e32 v151, 1.0, v151
	v_add_f32_e32 v152, 1.0, v152
	v_add_f32_e32 v153, 1.0, v153
	v_mul_f32_e32 v146, v146, v150
	v_mul_f32_e32 v147, v147, v151
	v_mul_f32_e32 v148, v148, v152
	v_mul_f32_e32 v149, v149, v153
	v_mul_f32_e32 v146, v180, v146
	v_mul_f32_e32 v147, v181, v147
	v_mul_f32_e32 v148, v182, v148
	v_mul_f32_e32 v149, v183, v149
	v_cvt_pk_bf16_f32 v150, v146, v147
	v_cvt_pk_bf16_f32 v151, v148, v149
	global_store_dwordx2 v130, v[150:151], s[24:25]
	s_add_u32 s24, s24, 0x800
	s_addc_u32 s25, s25, 0
	s_nop 0
	v_lshlrev_b32_e32 v146, 16, v198
	v_and_b32_e32 v147, 0xffff0000, v198
	v_lshlrev_b32_e32 v148, 16, v199
	v_and_b32_e32 v149, 0xffff0000, v199
	v_mul_f32_e32 v150, 0x3d372713, v146
	v_mul_f32_e32 v151, 0x3d372713, v147
	v_mul_f32_e32 v152, 0x3d372713, v148
	v_mul_f32_e32 v153, 0x3d372713, v149
	v_mul_f32_e32 v150, v150, v146
	v_mul_f32_e32 v151, v151, v147
	v_mul_f32_e32 v152, v152, v148
	v_mul_f32_e32 v153, v153, v149
	v_fma_f32 v150, v150, v146, v146
	v_fma_f32 v151, v151, v147, v147
	v_fma_f32 v152, v152, v148, v148
	v_fma_f32 v153, v153, v149, v149
	v_mul_f32_e32 v150, 0x3f4c422a, v150
	v_mul_f32_e32 v151, 0x3f4c422a, v151
	v_mul_f32_e32 v152, 0x3f4c422a, v152
	v_mul_f32_e32 v153, 0x3f4c422a, v153
	v_add_f32_e32 v150, v150, v150
	v_add_f32_e32 v151, v151, v151
	v_add_f32_e32 v152, v152, v152
	v_add_f32_e32 v153, v153, v153
	v_mul_f32_e32 v150, 0x3fb8aa3b, v150
	v_mul_f32_e32 v151, 0x3fb8aa3b, v151
	v_mul_f32_e32 v152, 0x3fb8aa3b, v152
	v_mul_f32_e32 v153, 0x3fb8aa3b, v153
	v_exp_f32_e32 v150, v150
	v_exp_f32_e32 v151, v151
	v_exp_f32_e32 v152, v152
	v_exp_f32_e32 v153, v153
	v_mul_f32_e32 v146, 0.5, v146
	v_mul_f32_e32 v147, 0.5, v147
	v_mul_f32_e32 v148, 0.5, v148
	v_mul_f32_e32 v149, 0.5, v149
	v_add_f32_e32 v150, 1.0, v150
	v_add_f32_e32 v151, 1.0, v151
	v_add_f32_e32 v152, 1.0, v152
	v_add_f32_e32 v153, 1.0, v153
	v_rcp_f32_e32 v150, v150
	v_rcp_f32_e32 v151, v151
	v_rcp_f32_e32 v152, v152
	v_rcp_f32_e32 v153, v153
	v_fmac_f32_e32 v190, v132, v194
	v_fmac_f32_e32 v191, v133, v195
	v_fmac_f32_e32 v192, v134, v196
	v_fmac_f32_e32 v193, v135, v197
	v_fma_f32 v150, v150, -2.0, 1.0
	v_fma_f32 v151, v151, -2.0, 1.0
	v_fma_f32 v152, v152, -2.0, 1.0
	v_fma_f32 v153, v153, -2.0, 1.0
	v_add_f32_e32 v150, 1.0, v150
	v_add_f32_e32 v151, 1.0, v151
	v_add_f32_e32 v152, 1.0, v152
	v_add_f32_e32 v153, 1.0, v153
	v_mul_f32_e32 v146, v146, v150
	v_mul_f32_e32 v147, v147, v151
	v_mul_f32_e32 v148, v148, v152
	v_mul_f32_e32 v149, v149, v153
	v_mul_f32_e32 v146, v190, v146
	v_mul_f32_e32 v147, v191, v147
	v_mul_f32_e32 v148, v192, v148
	v_mul_f32_e32 v149, v193, v149
	v_cvt_pk_bf16_f32 v150, v146, v147
	v_cvt_pk_bf16_f32 v151, v148, v149
	global_store_dwordx2 v130, v[150:151], s[24:25]
	s_add_u32 s24, s24, 0x800
	s_addc_u32 s25, s25, 0
	s_nop 0
	v_lshlrev_b32_e32 v146, 16, v208
	v_and_b32_e32 v147, 0xffff0000, v208
	v_lshlrev_b32_e32 v148, 16, v209
	v_and_b32_e32 v149, 0xffff0000, v209
	v_mul_f32_e32 v150, 0x3d372713, v146
	v_mul_f32_e32 v151, 0x3d372713, v147
	v_mul_f32_e32 v152, 0x3d372713, v148
	v_mul_f32_e32 v153, 0x3d372713, v149
	v_mul_f32_e32 v150, v150, v146
	v_mul_f32_e32 v151, v151, v147
	v_mul_f32_e32 v152, v152, v148
	v_mul_f32_e32 v153, v153, v149
	v_fma_f32 v150, v150, v146, v146
	v_fma_f32 v151, v151, v147, v147
	v_fma_f32 v152, v152, v148, v148
	v_fma_f32 v153, v153, v149, v149
	v_mul_f32_e32 v150, 0x3f4c422a, v150
	v_mul_f32_e32 v151, 0x3f4c422a, v151
	v_mul_f32_e32 v152, 0x3f4c422a, v152
	v_mul_f32_e32 v153, 0x3f4c422a, v153
	v_add_f32_e32 v150, v150, v150
	v_add_f32_e32 v151, v151, v151
	v_add_f32_e32 v152, v152, v152
	v_add_f32_e32 v153, v153, v153
	v_mul_f32_e32 v150, 0x3fb8aa3b, v150
	v_mul_f32_e32 v151, 0x3fb8aa3b, v151
	v_mul_f32_e32 v152, 0x3fb8aa3b, v152
	v_mul_f32_e32 v153, 0x3fb8aa3b, v153
	v_exp_f32_e32 v150, v150
	v_exp_f32_e32 v151, v151
	v_exp_f32_e32 v152, v152
	v_exp_f32_e32 v153, v153
	v_mul_f32_e32 v146, 0.5, v146
	v_mul_f32_e32 v147, 0.5, v147
	v_mul_f32_e32 v148, 0.5, v148
	v_mul_f32_e32 v149, 0.5, v149
	v_add_f32_e32 v150, 1.0, v150
	v_add_f32_e32 v151, 1.0, v151
	v_add_f32_e32 v152, 1.0, v152
	v_add_f32_e32 v153, 1.0, v153
	v_rcp_f32_e32 v150, v150
	v_rcp_f32_e32 v151, v151
	v_rcp_f32_e32 v152, v152
	v_rcp_f32_e32 v153, v153
	v_fmac_f32_e32 v200, v132, v204
	v_fmac_f32_e32 v201, v133, v205
	v_fmac_f32_e32 v202, v134, v206
	v_fmac_f32_e32 v203, v135, v207
	v_fma_f32 v150, v150, -2.0, 1.0
	v_fma_f32 v151, v151, -2.0, 1.0
	v_fma_f32 v152, v152, -2.0, 1.0
	v_fma_f32 v153, v153, -2.0, 1.0
	v_add_f32_e32 v150, 1.0, v150
	v_add_f32_e32 v151, 1.0, v151
	v_add_f32_e32 v152, 1.0, v152
	v_add_f32_e32 v153, 1.0, v153
	v_mul_f32_e32 v146, v146, v150
	v_mul_f32_e32 v147, v147, v151
	v_mul_f32_e32 v148, v148, v152
	v_mul_f32_e32 v149, v149, v153
	v_mul_f32_e32 v146, v200, v146
	v_mul_f32_e32 v147, v201, v147
	v_mul_f32_e32 v148, v202, v148
	v_mul_f32_e32 v149, v203, v149
	v_cvt_pk_bf16_f32 v150, v146, v147
	v_cvt_pk_bf16_f32 v151, v148, v149
	global_store_dwordx2 v130, v[150:151], s[24:25]
; __device__ __forceinline__ float bf2f(u16 h) { return __uint_as_float(((unsigned)h) << 16); }
; __device__ __forceinline__ float frcp_(float x) { return __builtin_amdgcn_rcpf(x); }
; __device__ __forceinline__ float tanhf_(float x) {
;   float e = __expf(2.0f * x);
;   return 1.0f - 2.0f * frcp_(1.0f + e);
; }
; __device__ __forceinline__ float geluf_(float x) {
;   float y = 0.7978845608028654f * (x + 0.044715f * x * x * x);
;   return 0.5f * x * (1.0f + tanhf_(y));
; }
; __device__ __forceinline__ void lru_fix_phase(const Params& p, const XcdBarrier& xb) {
;     ...
;       const int li = li0 + u;
;       const int r0 = li * 16;
; #pragma unroll 8
;       for (int q = 0; q < 16; q++) {
;         const int row = r0 + q;
;         float hv = HL[(size_t)row * 512 + ch] + CA[(size_t)row * 512 + ch] * carry;
;         float gate = geluf_(bf2f(Q[(size_t)row * 2048 + 1024 + ch]));
;         Y[(size_t)row * 1024 + 512 + ch] = f2bf(hv * gate);
	s_add_u32 s24, s24, 0x800
	s_addc_u32 s25, s25, 0
	s_nop 0
	v_lshlrev_b32_e32 v146, 16, v218
	v_and_b32_e32 v147, 0xffff0000, v218
	v_lshlrev_b32_e32 v148, 16, v219
	v_and_b32_e32 v149, 0xffff0000, v219
	v_mul_f32_e32 v150, 0x3d372713, v146
	v_mul_f32_e32 v151, 0x3d372713, v147
	v_mul_f32_e32 v152, 0x3d372713, v148
	v_mul_f32_e32 v153, 0x3d372713, v149
	v_mul_f32_e32 v150, v150, v146
	v_mul_f32_e32 v151, v151, v147
	v_mul_f32_e32 v152, v152, v148
	v_mul_f32_e32 v153, v153, v149
	v_fma_f32 v150, v150, v146, v146
	v_fma_f32 v151, v151, v147, v147
	v_fma_f32 v152, v152, v148, v148
	v_fma_f32 v153, v153, v149, v149
	v_mul_f32_e32 v150, 0x3f4c422a, v150
	v_mul_f32_e32 v151, 0x3f4c422a, v151
	v_mul_f32_e32 v152, 0x3f4c422a, v152
	v_mul_f32_e32 v153, 0x3f4c422a, v153
	v_add_f32_e32 v150, v150, v150
	v_add_f32_e32 v151, v151, v151
	v_add_f32_e32 v152, v152, v152
	v_add_f32_e32 v153, v153, v153
	v_mul_f32_e32 v150, 0x3fb8aa3b, v150
	v_mul_f32_e32 v151, 0x3fb8aa3b, v151
	v_mul_f32_e32 v152, 0x3fb8aa3b, v152
	v_mul_f32_e32 v153, 0x3fb8aa3b, v153
	v_exp_f32_e32 v150, v150
	v_exp_f32_e32 v151, v151
	v_exp_f32_e32 v152, v152
	v_exp_f32_e32 v153, v153
	v_mul_f32_e32 v146, 0.5, v146
	v_mul_f32_e32 v147, 0.5, v147
	v_mul_f32_e32 v148, 0.5, v148
	v_mul_f32_e32 v149, 0.5, v149
	v_add_f32_e32 v150, 1.0, v150
	v_add_f32_e32 v151, 1.0, v151
	v_add_f32_e32 v152, 1.0, v152
	v_add_f32_e32 v153, 1.0, v153
	v_rcp_f32_e32 v150, v150
	v_rcp_f32_e32 v151, v151
	v_rcp_f32_e32 v152, v152
	v_rcp_f32_e32 v153, v153
	v_fmac_f32_e32 v210, v132, v214
	v_fmac_f32_e32 v211, v133, v215
	v_fmac_f32_e32 v212, v134, v216
	v_fmac_f32_e32 v213, v135, v217
	v_fma_f32 v150, v150, -2.0, 1.0
	v_fma_f32 v151, v151, -2.0, 1.0
	v_fma_f32 v152, v152, -2.0, 1.0
	v_fma_f32 v153, v153, -2.0, 1.0
	v_add_f32_e32 v150, 1.0, v150
	v_add_f32_e32 v151, 1.0, v151
	v_add_f32_e32 v152, 1.0, v152
	v_add_f32_e32 v153, 1.0, v153
	v_mul_f32_e32 v146, v146, v150
	v_mul_f32_e32 v147, v147, v151
	v_mul_f32_e32 v148, v148, v152
	v_mul_f32_e32 v149, v149, v153
	v_mul_f32_e32 v146, v210, v146
	v_mul_f32_e32 v147, v211, v147
	v_mul_f32_e32 v148, v212, v148
	v_mul_f32_e32 v149, v213, v149
	v_cvt_pk_bf16_f32 v150, v146, v147
	v_cvt_pk_bf16_f32 v151, v148, v149
	global_store_dwordx2 v130, v[150:151], s[24:25]
	s_add_u32 s24, s24, 0x800
	s_addc_u32 s25, s25, 0
	s_nop 0
	v_lshlrev_b32_e32 v146, 16, v228
	v_and_b32_e32 v147, 0xffff0000, v228
	v_lshlrev_b32_e32 v148, 16, v229
	v_and_b32_e32 v149, 0xffff0000, v229
	v_mul_f32_e32 v150, 0x3d372713, v146
	v_mul_f32_e32 v151, 0x3d372713, v147
	v_mul_f32_e32 v152, 0x3d372713, v148
	v_mul_f32_e32 v153, 0x3d372713, v149
	v_mul_f32_e32 v150, v150, v146
	v_mul_f32_e32 v151, v151, v147
	v_mul_f32_e32 v152, v152, v148
	v_mul_f32_e32 v153, v153, v149
	v_fma_f32 v150, v150, v146, v146
	v_fma_f32 v151, v151, v147, v147
	v_fma_f32 v152, v152, v148, v148
	v_fma_f32 v153, v153, v149, v149
	v_mul_f32_e32 v150, 0x3f4c422a, v150
	v_mul_f32_e32 v151, 0x3f4c422a, v151
	v_mul_f32_e32 v152, 0x3f4c422a, v152
	v_mul_f32_e32 v153, 0x3f4c422a, v153
	v_add_f32_e32 v150, v150, v150
	v_add_f32_e32 v151, v151, v151
	v_add_f32_e32 v152, v152, v152
	v_add_f32_e32 v153, v153, v153
	v_mul_f32_e32 v150, 0x3fb8aa3b, v150
	v_mul_f32_e32 v151, 0x3fb8aa3b, v151
	v_mul_f32_e32 v152, 0x3fb8aa3b, v152
	v_mul_f32_e32 v153, 0x3fb8aa3b, v153
	v_exp_f32_e32 v150, v150
	v_exp_f32_e32 v151, v151
	v_exp_f32_e32 v152, v152
	v_exp_f32_e32 v153, v153
	v_mul_f32_e32 v146, 0.5, v146
	v_mul_f32_e32 v147, 0.5, v147
	v_mul_f32_e32 v148, 0.5, v148
	v_mul_f32_e32 v149, 0.5, v149
	v_add_f32_e32 v150, 1.0, v150
	v_add_f32_e32 v151, 1.0, v151
	v_add_f32_e32 v152, 1.0, v152
	v_add_f32_e32 v153, 1.0, v153
	v_rcp_f32_e32 v150, v150
	v_rcp_f32_e32 v151, v151
	v_rcp_f32_e32 v152, v152
	v_rcp_f32_e32 v153, v153
	v_fmac_f32_e32 v220, v132, v224
	v_fmac_f32_e32 v221, v133, v225
	v_fmac_f32_e32 v222, v134, v226
	v_fmac_f32_e32 v223, v135, v227
	v_fma_f32 v150, v150, -2.0, 1.0
	v_fma_f32 v151, v151, -2.0, 1.0
	v_fma_f32 v152, v152, -2.0, 1.0
	v_fma_f32 v153, v153, -2.0, 1.0
	v_add_f32_e32 v150, 1.0, v150
	v_add_f32_e32 v151, 1.0, v151
	v_add_f32_e32 v152, 1.0, v152
	v_add_f32_e32 v153, 1.0, v153
	v_mul_f32_e32 v146, v146, v150
	v_mul_f32_e32 v147, v147, v151
	v_mul_f32_e32 v148, v148, v152
	v_mul_f32_e32 v149, v149, v153
	v_mul_f32_e32 v146, v220, v146
	v_mul_f32_e32 v147, v221, v147
	v_mul_f32_e32 v148, v222, v148
	v_mul_f32_e32 v149, v223, v149
	v_cvt_pk_bf16_f32 v150, v146, v147
	v_cvt_pk_bf16_f32 v151, v148, v149
	global_store_dwordx2 v130, v[150:151], s[24:25]
	s_add_u32 s24, s24, 0x800
	s_addc_u32 s25, s25, 0
	s_nop 0
	v_lshlrev_b32_e32 v146, 16, v238
	v_and_b32_e32 v147, 0xffff0000, v238
	v_lshlrev_b32_e32 v148, 16, v239
	v_and_b32_e32 v149, 0xffff0000, v239
	v_mul_f32_e32 v150, 0x3d372713, v146
	v_mul_f32_e32 v151, 0x3d372713, v147
	v_mul_f32_e32 v152, 0x3d372713, v148
	v_mul_f32_e32 v153, 0x3d372713, v149
	v_mul_f32_e32 v150, v150, v146
	v_mul_f32_e32 v151, v151, v147
	v_mul_f32_e32 v152, v152, v148
	v_mul_f32_e32 v153, v153, v149
	v_fma_f32 v150, v150, v146, v146
	v_fma_f32 v151, v151, v147, v147
	v_fma_f32 v152, v152, v148, v148
	v_fma_f32 v153, v153, v149, v149
	v_mul_f32_e32 v150, 0x3f4c422a, v150
	v_mul_f32_e32 v151, 0x3f4c422a, v151
	v_mul_f32_e32 v152, 0x3f4c422a, v152
	v_mul_f32_e32 v153, 0x3f4c422a, v153
	v_add_f32_e32 v150, v150, v150
	v_add_f32_e32 v151, v151, v151
	v_add_f32_e32 v152, v152, v152
	v_add_f32_e32 v153, v153, v153
	v_mul_f32_e32 v150, 0x3fb8aa3b, v150
	v_mul_f32_e32 v151, 0x3fb8aa3b, v151
	v_mul_f32_e32 v152, 0x3fb8aa3b, v152
	v_mul_f32_e32 v153, 0x3fb8aa3b, v153
	v_exp_f32_e32 v150, v150
	v_exp_f32_e32 v151, v151
	v_exp_f32_e32 v152, v152
	v_exp_f32_e32 v153, v153
	v_mul_f32_e32 v146, 0.5, v146
	v_mul_f32_e32 v147, 0.5, v147
	v_mul_f32_e32 v148, 0.5, v148
	v_mul_f32_e32 v149, 0.5, v149
	v_add_f32_e32 v150, 1.0, v150
	v_add_f32_e32 v151, 1.0, v151
	v_add_f32_e32 v152, 1.0, v152
	v_add_f32_e32 v153, 1.0, v153
	v_rcp_f32_e32 v150, v150
	v_rcp_f32_e32 v151, v151
	v_rcp_f32_e32 v152, v152
	v_rcp_f32_e32 v153, v153
	v_fmac_f32_e32 v230, v132, v234
	v_fmac_f32_e32 v231, v133, v235
	v_fmac_f32_e32 v232, v134, v236
	v_fmac_f32_e32 v233, v135, v237
	v_fma_f32 v150, v150, -2.0, 1.0
	v_fma_f32 v151, v151, -2.0, 1.0
	v_fma_f32 v152, v152, -2.0, 1.0
	v_fma_f32 v153, v153, -2.0, 1.0
	v_add_f32_e32 v150, 1.0, v150
	v_add_f32_e32 v151, 1.0, v151
	v_add_f32_e32 v152, 1.0, v152
	v_add_f32_e32 v153, 1.0, v153
	v_mul_f32_e32 v146, v146, v150
	v_mul_f32_e32 v147, v147, v151
	v_mul_f32_e32 v148, v148, v152
	v_mul_f32_e32 v149, v149, v153
	v_mul_f32_e32 v146, v230, v146
	v_mul_f32_e32 v147, v231, v147
	v_mul_f32_e32 v148, v232, v148
	v_mul_f32_e32 v149, v233, v149
	v_cvt_pk_bf16_f32 v150, v146, v147
	v_cvt_pk_bf16_f32 v151, v148, v149
	global_store_dwordx2 v130, v[150:151], s[24:25]
	s_add_u32 s24, s24, 0x800
	s_addc_u32 s25, s25, 0
	s_nop 0
	s_waitcnt vmcnt(8)
; __device__ __forceinline__ float bf2f(u16 h) { return __uint_as_float(((unsigned)h) << 16); }
; __device__ __forceinline__ float frcp_(float x) { return __builtin_amdgcn_rcpf(x); }
; __device__ __forceinline__ float tanhf_(float x) {
;   float e = __expf(2.0f * x);
;   return 1.0f - 2.0f * frcp_(1.0f + e);
; }
; __device__ __forceinline__ float geluf_(float x) {
;   float y = 0.7978845608028654f * (x + 0.044715f * x * x * x);
;   return 0.5f * x * (1.0f + tanhf_(y));
; }
; __device__ __forceinline__ void lru_fix_phase(const Params& p, const XcdBarrier& xb) {
;     ...
;       const int li = li0 + u;
;       const int r0 = li * 16;
; #pragma unroll 8
;       for (int q = 0; q < 16; q++) {
;         const int row = r0 + q;
;         float hv = HL[(size_t)row * 512 + ch] + CA[(size_t)row * 512 + ch] * carry;
;         float gate = geluf_(bf2f(Q[(size_t)row * 2048 + 1024 + ch]));
;         Y[(size_t)row * 1024 + 512 + ch] = f2bf(hv * gate);
	v_lshlrev_b32_e32 v146, 16, v8
	v_and_b32_e32 v147, 0xffff0000, v8
	v_lshlrev_b32_e32 v148, 16, v9
	v_and_b32_e32 v149, 0xffff0000, v9
	v_mul_f32_e32 v150, 0x3d372713, v146
	v_mul_f32_e32 v151, 0x3d372713, v147
	v_mul_f32_e32 v152, 0x3d372713, v148
	v_mul_f32_e32 v153, 0x3d372713, v149
	v_mul_f32_e32 v150, v150, v146
	v_mul_f32_e32 v151, v151, v147
	v_mul_f32_e32 v152, v152, v148
	v_mul_f32_e32 v153, v153, v149
	v_fma_f32 v150, v150, v146, v146
	v_fma_f32 v151, v151, v147, v147
	v_fma_f32 v152, v152, v148, v148
	v_fma_f32 v153, v153, v149, v149
	v_mul_f32_e32 v150, 0x3f4c422a, v150
	v_mul_f32_e32 v151, 0x3f4c422a, v151
	v_mul_f32_e32 v152, 0x3f4c422a, v152
	v_mul_f32_e32 v153, 0x3f4c422a, v153
	v_add_f32_e32 v150, v150, v150
	v_add_f32_e32 v151, v151, v151
	v_add_f32_e32 v152, v152, v152
	v_add_f32_e32 v153, v153, v153
	v_mul_f32_e32 v150, 0x3fb8aa3b, v150
	v_mul_f32_e32 v151, 0x3fb8aa3b, v151
	v_mul_f32_e32 v152, 0x3fb8aa3b, v152
	v_mul_f32_e32 v153, 0x3fb8aa3b, v153
	v_exp_f32_e32 v150, v150
	v_exp_f32_e32 v151, v151
	v_exp_f32_e32 v152, v152
	v_exp_f32_e32 v153, v153
	v_mul_f32_e32 v146, 0.5, v146
	v_mul_f32_e32 v147, 0.5, v147
	v_mul_f32_e32 v148, 0.5, v148
	v_mul_f32_e32 v149, 0.5, v149
	v_add_f32_e32 v150, 1.0, v150
	v_add_f32_e32 v151, 1.0, v151
	v_add_f32_e32 v152, 1.0, v152
	v_add_f32_e32 v153, 1.0, v153
	v_rcp_f32_e32 v150, v150
	v_rcp_f32_e32 v151, v151
	v_rcp_f32_e32 v152, v152
	v_rcp_f32_e32 v153, v153
	v_fmac_f32_e32 v0, v132, v4
	v_fmac_f32_e32 v1, v133, v5
	v_fmac_f32_e32 v2, v134, v6
	v_fmac_f32_e32 v3, v135, v7
	v_fma_f32 v150, v150, -2.0, 1.0
	v_fma_f32 v151, v151, -2.0, 1.0
	v_fma_f32 v152, v152, -2.0, 1.0
	v_fma_f32 v153, v153, -2.0, 1.0
	v_add_f32_e32 v150, 1.0, v150
	v_add_f32_e32 v151, 1.0, v151
	v_add_f32_e32 v152, 1.0, v152
	v_add_f32_e32 v153, 1.0, v153
	v_mul_f32_e32 v146, v146, v150
	v_mul_f32_e32 v147, v147, v151
	v_mul_f32_e32 v148, v148, v152
	v_mul_f32_e32 v149, v149, v153
	v_mul_f32_e32 v146, v0, v146
	v_mul_f32_e32 v147, v1, v147
	v_mul_f32_e32 v148, v2, v148
	v_mul_f32_e32 v149, v3, v149
	v_cvt_pk_bf16_f32 v150, v146, v147
	v_cvt_pk_bf16_f32 v151, v148, v149
	global_store_dwordx2 v130, v[150:151], s[24:25]
	s_add_u32 s24, s24, 0x800
	s_addc_u32 s25, s25, 0
	s_nop 0
	v_lshlrev_b32_e32 v146, 16, v18
	v_and_b32_e32 v147, 0xffff0000, v18
	v_lshlrev_b32_e32 v148, 16, v19
	v_and_b32_e32 v149, 0xffff0000, v19
	v_mul_f32_e32 v150, 0x3d372713, v146
	v_mul_f32_e32 v151, 0x3d372713, v147
	v_mul_f32_e32 v152, 0x3d372713, v148
	v_mul_f32_e32 v153, 0x3d372713, v149
	v_mul_f32_e32 v150, v150, v146
	v_mul_f32_e32 v151, v151, v147
	v_mul_f32_e32 v152, v152, v148
	v_mul_f32_e32 v153, v153, v149
	v_fma_f32 v150, v150, v146, v146
	v_fma_f32 v151, v151, v147, v147
	v_fma_f32 v152, v152, v148, v148
	v_fma_f32 v153, v153, v149, v149
	v_mul_f32_e32 v150, 0x3f4c422a, v150
	v_mul_f32_e32 v151, 0x3f4c422a, v151
	v_mul_f32_e32 v152, 0x3f4c422a, v152
	v_mul_f32_e32 v153, 0x3f4c422a, v153
	v_add_f32_e32 v150, v150, v150
	v_add_f32_e32 v151, v151, v151
	v_add_f32_e32 v152, v152, v152
	v_add_f32_e32 v153, v153, v153
	v_mul_f32_e32 v150, 0x3fb8aa3b, v150
	v_mul_f32_e32 v151, 0x3fb8aa3b, v151
	v_mul_f32_e32 v152, 0x3fb8aa3b, v152
	v_mul_f32_e32 v153, 0x3fb8aa3b, v153
	v_exp_f32_e32 v150, v150
	v_exp_f32_e32 v151, v151
	v_exp_f32_e32 v152, v152
	v_exp_f32_e32 v153, v153
	v_mul_f32_e32 v146, 0.5, v146
	v_mul_f32_e32 v147, 0.5, v147
	v_mul_f32_e32 v148, 0.5, v148
	v_mul_f32_e32 v149, 0.5, v149
	v_add_f32_e32 v150, 1.0, v150
	v_add_f32_e32 v151, 1.0, v151
	v_add_f32_e32 v152, 1.0, v152
	v_add_f32_e32 v153, 1.0, v153
	v_rcp_f32_e32 v150, v150
	v_rcp_f32_e32 v151, v151
	v_rcp_f32_e32 v152, v152
	v_rcp_f32_e32 v153, v153
	v_fmac_f32_e32 v10, v132, v14
	v_fmac_f32_e32 v11, v133, v15
	v_fmac_f32_e32 v12, v134, v16
	v_fmac_f32_e32 v13, v135, v17
	v_fma_f32 v150, v150, -2.0, 1.0
	v_fma_f32 v151, v151, -2.0, 1.0
	v_fma_f32 v152, v152, -2.0, 1.0
	v_fma_f32 v153, v153, -2.0, 1.0
	v_add_f32_e32 v150, 1.0, v150
	v_add_f32_e32 v151, 1.0, v151
	v_add_f32_e32 v152, 1.0, v152
	v_add_f32_e32 v153, 1.0, v153
	v_mul_f32_e32 v146, v146, v150
	v_mul_f32_e32 v147, v147, v151
	v_mul_f32_e32 v148, v148, v152
	v_mul_f32_e32 v149, v149, v153
	v_mul_f32_e32 v146, v10, v146
	v_mul_f32_e32 v147, v11, v147
	v_mul_f32_e32 v148, v12, v148
	v_mul_f32_e32 v149, v13, v149
	v_cvt_pk_bf16_f32 v150, v146, v147
	v_cvt_pk_bf16_f32 v151, v148, v149
	global_store_dwordx2 v130, v[150:151], s[24:25]
	s_add_u32 s24, s24, 0x800
	s_addc_u32 s25, s25, 0
	s_nop 0
	v_lshlrev_b32_e32 v146, 16, v28
	v_and_b32_e32 v147, 0xffff0000, v28
	v_lshlrev_b32_e32 v148, 16, v29
	v_and_b32_e32 v149, 0xffff0000, v29
	v_mul_f32_e32 v150, 0x3d372713, v146
	v_mul_f32_e32 v151, 0x3d372713, v147
	v_mul_f32_e32 v152, 0x3d372713, v148
	v_mul_f32_e32 v153, 0x3d372713, v149
	v_mul_f32_e32 v150, v150, v146
	v_mul_f32_e32 v151, v151, v147
	v_mul_f32_e32 v152, v152, v148
	v_mul_f32_e32 v153, v153, v149
	v_fma_f32 v150, v150, v146, v146
	v_fma_f32 v151, v151, v147, v147
	v_fma_f32 v152, v152, v148, v148
	v_fma_f32 v153, v153, v149, v149
	v_mul_f32_e32 v150, 0x3f4c422a, v150
	v_mul_f32_e32 v151, 0x3f4c422a, v151
	v_mul_f32_e32 v152, 0x3f4c422a, v152
	v_mul_f32_e32 v153, 0x3f4c422a, v153
	v_add_f32_e32 v150, v150, v150
	v_add_f32_e32 v151, v151, v151
	v_add_f32_e32 v152, v152, v152
	v_add_f32_e32 v153, v153, v153
	v_mul_f32_e32 v150, 0x3fb8aa3b, v150
	v_mul_f32_e32 v151, 0x3fb8aa3b, v151
	v_mul_f32_e32 v152, 0x3fb8aa3b, v152
	v_mul_f32_e32 v153, 0x3fb8aa3b, v153
	v_exp_f32_e32 v150, v150
	v_exp_f32_e32 v151, v151
	v_exp_f32_e32 v152, v152
	v_exp_f32_e32 v153, v153
	v_mul_f32_e32 v146, 0.5, v146
	v_mul_f32_e32 v147, 0.5, v147
; __device__ __forceinline__ float bf2f(u16 h) { return __uint_as_float(((unsigned)h) << 16); }
; __device__ __forceinline__ float frcp_(float x) { return __builtin_amdgcn_rcpf(x); }
; __device__ __forceinline__ float tanhf_(float x) {
;   float e = __expf(2.0f * x);
;   return 1.0f - 2.0f * frcp_(1.0f + e);
; }
; __device__ __forceinline__ float geluf_(float x) {
;   float y = 0.7978845608028654f * (x + 0.044715f * x * x * x);
;   return 0.5f * x * (1.0f + tanhf_(y));
; }
; __device__ __forceinline__ void lru_fix_phase(const Params& p, const XcdBarrier& xb) {
;     ...
;       const int li = li0 + u;
;       const int r0 = li * 16;
; #pragma unroll 8
;       for (int q = 0; q < 16; q++) {
;         const int row = r0 + q;
;         float hv = HL[(size_t)row * 512 + ch] + CA[(size_t)row * 512 + ch] * carry;
;         float gate = geluf_(bf2f(Q[(size_t)row * 2048 + 1024 + ch]));
;         Y[(size_t)row * 1024 + 512 + ch] = f2bf(hv * gate);
	v_mul_f32_e32 v148, 0.5, v148
	v_mul_f32_e32 v149, 0.5, v149
	v_add_f32_e32 v150, 1.0, v150
	v_add_f32_e32 v151, 1.0, v151
	v_add_f32_e32 v152, 1.0, v152
	v_add_f32_e32 v153, 1.0, v153
	v_rcp_f32_e32 v150, v150
	v_rcp_f32_e32 v151, v151
	v_rcp_f32_e32 v152, v152
	v_rcp_f32_e32 v153, v153
	v_fmac_f32_e32 v20, v132, v24
	v_fmac_f32_e32 v21, v133, v25
	v_fmac_f32_e32 v22, v134, v26
	v_fmac_f32_e32 v23, v135, v27
	v_fma_f32 v150, v150, -2.0, 1.0
	v_fma_f32 v151, v151, -2.0, 1.0
	v_fma_f32 v152, v152, -2.0, 1.0
	v_fma_f32 v153, v153, -2.0, 1.0
	v_add_f32_e32 v150, 1.0, v150
	v_add_f32_e32 v151, 1.0, v151
	v_add_f32_e32 v152, 1.0, v152
	v_add_f32_e32 v153, 1.0, v153
	v_mul_f32_e32 v146, v146, v150
	v_mul_f32_e32 v147, v147, v151
	v_mul_f32_e32 v148, v148, v152
	v_mul_f32_e32 v149, v149, v153
	v_mul_f32_e32 v146, v20, v146
	v_mul_f32_e32 v147, v21, v147
	v_mul_f32_e32 v148, v22, v148
	v_mul_f32_e32 v149, v23, v149
	v_cvt_pk_bf16_f32 v150, v146, v147
	v_cvt_pk_bf16_f32 v151, v148, v149
	global_store_dwordx2 v130, v[150:151], s[24:25]
	s_add_u32 s24, s24, 0x800
	s_addc_u32 s25, s25, 0
	s_nop 0
	v_lshlrev_b32_e32 v146, 16, v38
	v_and_b32_e32 v147, 0xffff0000, v38
	v_lshlrev_b32_e32 v148, 16, v39
	v_and_b32_e32 v149, 0xffff0000, v39
	v_mul_f32_e32 v150, 0x3d372713, v146
	v_mul_f32_e32 v151, 0x3d372713, v147
	v_mul_f32_e32 v152, 0x3d372713, v148
	v_mul_f32_e32 v153, 0x3d372713, v149
	v_mul_f32_e32 v150, v150, v146
	v_mul_f32_e32 v151, v151, v147
	v_mul_f32_e32 v152, v152, v148
	v_mul_f32_e32 v153, v153, v149
	v_fma_f32 v150, v150, v146, v146
	v_fma_f32 v151, v151, v147, v147
	v_fma_f32 v152, v152, v148, v148
	v_fma_f32 v153, v153, v149, v149
	v_mul_f32_e32 v150, 0x3f4c422a, v150
	v_mul_f32_e32 v151, 0x3f4c422a, v151
	v_mul_f32_e32 v152, 0x3f4c422a, v152
	v_mul_f32_e32 v153, 0x3f4c422a, v153
	v_add_f32_e32 v150, v150, v150
	v_add_f32_e32 v151, v151, v151
	v_add_f32_e32 v152, v152, v152
	v_add_f32_e32 v153, v153, v153
	v_mul_f32_e32 v150, 0x3fb8aa3b, v150
	v_mul_f32_e32 v151, 0x3fb8aa3b, v151
	v_mul_f32_e32 v152, 0x3fb8aa3b, v152
	v_mul_f32_e32 v153, 0x3fb8aa3b, v153
	v_exp_f32_e32 v150, v150
	v_exp_f32_e32 v151, v151
	v_exp_f32_e32 v152, v152
	v_exp_f32_e32 v153, v153
	v_mul_f32_e32 v146, 0.5, v146
	v_mul_f32_e32 v147, 0.5, v147
	v_mul_f32_e32 v148, 0.5, v148
	v_mul_f32_e32 v149, 0.5, v149
	v_add_f32_e32 v150, 1.0, v150
	v_add_f32_e32 v151, 1.0, v151
	v_add_f32_e32 v152, 1.0, v152
	v_add_f32_e32 v153, 1.0, v153
	v_rcp_f32_e32 v150, v150
	v_rcp_f32_e32 v151, v151
	v_rcp_f32_e32 v152, v152
	v_rcp_f32_e32 v153, v153
	v_fmac_f32_e32 v30, v132, v34
	v_fmac_f32_e32 v31, v133, v35
	v_fmac_f32_e32 v32, v134, v36
	v_fmac_f32_e32 v33, v135, v37
	v_fma_f32 v150, v150, -2.0, 1.0
	v_fma_f32 v151, v151, -2.0, 1.0
	v_fma_f32 v152, v152, -2.0, 1.0
	v_fma_f32 v153, v153, -2.0, 1.0
	v_add_f32_e32 v150, 1.0, v150
	v_add_f32_e32 v151, 1.0, v151
	v_add_f32_e32 v152, 1.0, v152
	v_add_f32_e32 v153, 1.0, v153
	v_mul_f32_e32 v146, v146, v150
	v_mul_f32_e32 v147, v147, v151
	v_mul_f32_e32 v148, v148, v152
	v_mul_f32_e32 v149, v149, v153
	v_mul_f32_e32 v146, v30, v146
	v_mul_f32_e32 v147, v31, v147
	v_mul_f32_e32 v148, v32, v148
	v_mul_f32_e32 v149, v33, v149
	v_cvt_pk_bf16_f32 v150, v146, v147
	v_cvt_pk_bf16_f32 v151, v148, v149
	global_store_dwordx2 v130, v[150:151], s[24:25]
	s_add_u32 s24, s24, 0x800
	s_addc_u32 s25, s25, 0
	s_nop 0
	v_lshlrev_b32_e32 v146, 16, v48
	v_and_b32_e32 v147, 0xffff0000, v48
	v_lshlrev_b32_e32 v148, 16, v49
	v_and_b32_e32 v149, 0xffff0000, v49
	v_mul_f32_e32 v150, 0x3d372713, v146
	v_mul_f32_e32 v151, 0x3d372713, v147
	v_mul_f32_e32 v152, 0x3d372713, v148
	v_mul_f32_e32 v153, 0x3d372713, v149
	v_mul_f32_e32 v150, v150, v146
	v_mul_f32_e32 v151, v151, v147
	v_mul_f32_e32 v152, v152, v148
	v_mul_f32_e32 v153, v153, v149
	v_fma_f32 v150, v150, v146, v146
	v_fma_f32 v151, v151, v147, v147
	v_fma_f32 v152, v152, v148, v148
	v_fma_f32 v153, v153, v149, v149
	v_mul_f32_e32 v150, 0x3f4c422a, v150
	v_mul_f32_e32 v151, 0x3f4c422a, v151
	v_mul_f32_e32 v152, 0x3f4c422a, v152
	v_mul_f32_e32 v153, 0x3f4c422a, v153
	v_add_f32_e32 v150, v150, v150
	v_add_f32_e32 v151, v151, v151
	v_add_f32_e32 v152, v152, v152
	v_add_f32_e32 v153, v153, v153
	v_mul_f32_e32 v150, 0x3fb8aa3b, v150
	v_mul_f32_e32 v151, 0x3fb8aa3b, v151
	v_mul_f32_e32 v152, 0x3fb8aa3b, v152
	v_mul_f32_e32 v153, 0x3fb8aa3b, v153
	v_exp_f32_e32 v150, v150
	v_exp_f32_e32 v151, v151
	v_exp_f32_e32 v152, v152
	v_exp_f32_e32 v153, v153
	v_mul_f32_e32 v146, 0.5, v146
	v_mul_f32_e32 v147, 0.5, v147
	v_mul_f32_e32 v148, 0.5, v148
	v_mul_f32_e32 v149, 0.5, v149
	v_add_f32_e32 v150, 1.0, v150
	v_add_f32_e32 v151, 1.0, v151
	v_add_f32_e32 v152, 1.0, v152
	v_add_f32_e32 v153, 1.0, v153
	v_rcp_f32_e32 v150, v150
	v_rcp_f32_e32 v151, v151
	v_rcp_f32_e32 v152, v152
	v_rcp_f32_e32 v153, v153
	v_fmac_f32_e32 v40, v132, v44
	v_fmac_f32_e32 v41, v133, v45
	v_fmac_f32_e32 v42, v134, v46
	v_fmac_f32_e32 v43, v135, v47
	v_fma_f32 v150, v150, -2.0, 1.0
	v_fma_f32 v151, v151, -2.0, 1.0
	v_fma_f32 v152, v152, -2.0, 1.0
	v_fma_f32 v153, v153, -2.0, 1.0
	v_add_f32_e32 v150, 1.0, v150
	v_add_f32_e32 v151, 1.0, v151
	v_add_f32_e32 v152, 1.0, v152
	v_add_f32_e32 v153, 1.0, v153
	v_mul_f32_e32 v146, v146, v150
	v_mul_f32_e32 v147, v147, v151
	v_mul_f32_e32 v148, v148, v152
	v_mul_f32_e32 v149, v149, v153
	v_mul_f32_e32 v146, v40, v146
	v_mul_f32_e32 v147, v41, v147
	v_mul_f32_e32 v148, v42, v148
	v_mul_f32_e32 v149, v43, v149
	v_cvt_pk_bf16_f32 v150, v146, v147
	v_cvt_pk_bf16_f32 v151, v148, v149
	global_store_dwordx2 v130, v[150:151], s[24:25]
	s_add_u32 s24, s24, 0x800
	s_addc_u32 s25, s25, 0
	s_nop 0
	v_lshlrev_b32_e32 v146, 16, v58
; __device__ __forceinline__ float bf2f(u16 h) { return __uint_as_float(((unsigned)h) << 16); }
; __device__ __forceinline__ void lru_fix_phase(const Params& p, const XcdBarrier& xb) {
;     ...
;       const int li = li0 + u;
;       const int r0 = li * 16;
; #pragma unroll 8
;       for (int q = 0; q < 16; q++) {
;         const int row = r0 + q;
;         float hv = HL[(size_t)row * 512 + ch] + CA[(size_t)row * 512 + ch] * carry;
;         float gate = geluf_(bf2f(Q[(size_t)row * 2048 + 1024 + ch]));
;         Y[(size_t)row * 1024 + 512 + ch] = f2bf(hv * gate);
;         if ((row & 2047) == 2047) p.out[OUT_PLRU + (size_t)(row >> 11) * 512 + ch] = hv;
	v_and_b32_e32 v147, 0xffff0000, v58
	v_lshlrev_b32_e32 v148, 16, v59
	v_and_b32_e32 v149, 0xffff0000, v59
	v_mul_f32_e32 v150, 0x3d372713, v146
	v_mul_f32_e32 v151, 0x3d372713, v147
	v_mul_f32_e32 v152, 0x3d372713, v148
	v_mul_f32_e32 v153, 0x3d372713, v149
	v_mul_f32_e32 v150, v150, v146
	v_mul_f32_e32 v151, v151, v147
	v_mul_f32_e32 v152, v152, v148
	v_mul_f32_e32 v153, v153, v149
	v_fma_f32 v150, v150, v146, v146
	v_fma_f32 v151, v151, v147, v147
	v_fma_f32 v152, v152, v148, v148
	v_fma_f32 v153, v153, v149, v149
	v_mul_f32_e32 v150, 0x3f4c422a, v150
	v_mul_f32_e32 v151, 0x3f4c422a, v151
	v_mul_f32_e32 v152, 0x3f4c422a, v152
	v_mul_f32_e32 v153, 0x3f4c422a, v153
	v_add_f32_e32 v150, v150, v150
	v_add_f32_e32 v151, v151, v151
	v_add_f32_e32 v152, v152, v152
	v_add_f32_e32 v153, v153, v153
	v_mul_f32_e32 v150, 0x3fb8aa3b, v150
	v_mul_f32_e32 v151, 0x3fb8aa3b, v151
	v_mul_f32_e32 v152, 0x3fb8aa3b, v152
	v_mul_f32_e32 v153, 0x3fb8aa3b, v153
	v_exp_f32_e32 v150, v150
	v_exp_f32_e32 v151, v151
	v_exp_f32_e32 v152, v152
	v_exp_f32_e32 v153, v153
	v_mul_f32_e32 v146, 0.5, v146
	v_mul_f32_e32 v147, 0.5, v147
	v_mul_f32_e32 v148, 0.5, v148
	v_mul_f32_e32 v149, 0.5, v149
	v_add_f32_e32 v150, 1.0, v150
	v_add_f32_e32 v151, 1.0, v151
	v_add_f32_e32 v152, 1.0, v152
	v_add_f32_e32 v153, 1.0, v153
	v_rcp_f32_e32 v150, v150
	v_rcp_f32_e32 v151, v151
	v_rcp_f32_e32 v152, v152
	v_rcp_f32_e32 v153, v153
	v_fmac_f32_e32 v50, v132, v54
	v_fmac_f32_e32 v51, v133, v55
	v_fmac_f32_e32 v52, v134, v56
	v_fmac_f32_e32 v53, v135, v57
	v_fma_f32 v150, v150, -2.0, 1.0
	v_fma_f32 v151, v151, -2.0, 1.0
	v_fma_f32 v152, v152, -2.0, 1.0
	v_fma_f32 v153, v153, -2.0, 1.0
	v_add_f32_e32 v150, 1.0, v150
	v_add_f32_e32 v151, 1.0, v151
	v_add_f32_e32 v152, 1.0, v152
	v_add_f32_e32 v153, 1.0, v153
	v_mul_f32_e32 v146, v146, v150
	v_mul_f32_e32 v147, v147, v151
	v_mul_f32_e32 v148, v148, v152
	v_mul_f32_e32 v149, v149, v153
	v_mul_f32_e32 v146, v50, v146
	v_mul_f32_e32 v147, v51, v147
	v_mul_f32_e32 v148, v52, v148
	v_mul_f32_e32 v149, v53, v149
	v_cvt_pk_bf16_f32 v150, v146, v147
	v_cvt_pk_bf16_f32 v151, v148, v149
	global_store_dwordx2 v130, v[150:151], s[24:25]
	s_add_u32 s24, s24, 0x800
	s_addc_u32 s25, s25, 0
	s_nop 0
	v_lshlrev_b32_e32 v146, 16, v68
	v_and_b32_e32 v147, 0xffff0000, v68
	v_lshlrev_b32_e32 v148, 16, v69
	v_and_b32_e32 v149, 0xffff0000, v69
	v_mul_f32_e32 v150, 0x3d372713, v146
	v_mul_f32_e32 v151, 0x3d372713, v147
	v_mul_f32_e32 v152, 0x3d372713, v148
	v_mul_f32_e32 v153, 0x3d372713, v149
	v_mul_f32_e32 v150, v150, v146
	v_mul_f32_e32 v151, v151, v147
	v_mul_f32_e32 v152, v152, v148
	v_mul_f32_e32 v153, v153, v149
	v_fma_f32 v150, v150, v146, v146
	v_fma_f32 v151, v151, v147, v147
	v_fma_f32 v152, v152, v148, v148
	v_fma_f32 v153, v153, v149, v149
	v_mul_f32_e32 v150, 0x3f4c422a, v150
	v_mul_f32_e32 v151, 0x3f4c422a, v151
	v_mul_f32_e32 v152, 0x3f4c422a, v152
	v_mul_f32_e32 v153, 0x3f4c422a, v153
	v_add_f32_e32 v150, v150, v150
	v_add_f32_e32 v151, v151, v151
	v_add_f32_e32 v152, v152, v152
	v_add_f32_e32 v153, v153, v153
	v_mul_f32_e32 v150, 0x3fb8aa3b, v150
	v_mul_f32_e32 v151, 0x3fb8aa3b, v151
	v_mul_f32_e32 v152, 0x3fb8aa3b, v152
	v_mul_f32_e32 v153, 0x3fb8aa3b, v153
	v_exp_f32_e32 v150, v150
	v_exp_f32_e32 v151, v151
	v_exp_f32_e32 v152, v152
	v_exp_f32_e32 v153, v153
	v_mul_f32_e32 v146, 0.5, v146
	v_mul_f32_e32 v147, 0.5, v147
	v_mul_f32_e32 v148, 0.5, v148
	v_mul_f32_e32 v149, 0.5, v149
	v_add_f32_e32 v150, 1.0, v150
	v_add_f32_e32 v151, 1.0, v151
	v_add_f32_e32 v152, 1.0, v152
	v_add_f32_e32 v153, 1.0, v153
	v_rcp_f32_e32 v150, v150
	v_rcp_f32_e32 v151, v151
	v_rcp_f32_e32 v152, v152
	v_rcp_f32_e32 v153, v153
	v_fmac_f32_e32 v60, v132, v64
	v_fmac_f32_e32 v61, v133, v65
	v_fmac_f32_e32 v62, v134, v66
	v_fmac_f32_e32 v63, v135, v67
	v_fma_f32 v150, v150, -2.0, 1.0
	v_fma_f32 v151, v151, -2.0, 1.0
	v_fma_f32 v152, v152, -2.0, 1.0
	v_fma_f32 v153, v153, -2.0, 1.0
	v_add_f32_e32 v150, 1.0, v150
	v_add_f32_e32 v151, 1.0, v151
	v_add_f32_e32 v152, 1.0, v152
	v_add_f32_e32 v153, 1.0, v153
	v_mul_f32_e32 v146, v146, v150
	v_mul_f32_e32 v147, v147, v151
	v_mul_f32_e32 v148, v148, v152
	v_mul_f32_e32 v149, v149, v153
	v_mul_f32_e32 v146, v60, v146
	v_mul_f32_e32 v147, v61, v147
	v_mul_f32_e32 v148, v62, v148
	v_mul_f32_e32 v149, v63, v149
	v_cvt_pk_bf16_f32 v150, v146, v147
	v_cvt_pk_bf16_f32 v151, v148, v149
	global_store_dwordx2 v130, v[150:151], s[24:25]
	s_add_u32 s24, s24, 0x800
	s_addc_u32 s25, s25, 0
	s_nop 0
	v_lshlrev_b32_e32 v146, 16, v78
	v_and_b32_e32 v147, 0xffff0000, v78
	v_lshlrev_b32_e32 v148, 16, v79
	v_and_b32_e32 v149, 0xffff0000, v79
	v_mul_f32_e32 v150, 0x3d372713, v146
	v_mul_f32_e32 v151, 0x3d372713, v147
	v_mul_f32_e32 v152, 0x3d372713, v148
	v_mul_f32_e32 v153, 0x3d372713, v149
	v_mul_f32_e32 v150, v150, v146
	v_mul_f32_e32 v151, v151, v147
	v_mul_f32_e32 v152, v152, v148
	v_mul_f32_e32 v153, v153, v149
	v_fma_f32 v150, v150, v146, v146
	v_fma_f32 v151, v151, v147, v147
	v_fma_f32 v152, v152, v148, v148
	v_fma_f32 v153, v153, v149, v149
	v_mul_f32_e32 v150, 0x3f4c422a, v150
	v_mul_f32_e32 v151, 0x3f4c422a, v151
	v_mul_f32_e32 v152, 0x3f4c422a, v152
	v_mul_f32_e32 v153, 0x3f4c422a, v153
	v_add_f32_e32 v150, v150, v150
	v_add_f32_e32 v151, v151, v151
	v_add_f32_e32 v152, v152, v152
	v_add_f32_e32 v153, v153, v153
	v_mul_f32_e32 v150, 0x3fb8aa3b, v150
	v_mul_f32_e32 v151, 0x3fb8aa3b, v151
	v_mul_f32_e32 v152, 0x3fb8aa3b, v152
	v_mul_f32_e32 v153, 0x3fb8aa3b, v153
	v_exp_f32_e32 v150, v150
	v_exp_f32_e32 v151, v151
	v_exp_f32_e32 v152, v152
	v_exp_f32_e32 v153, v153
	v_mul_f32_e32 v146, 0.5, v146
	v_mul_f32_e32 v147, 0.5, v147
	v_mul_f32_e32 v148, 0.5, v148
	v_mul_f32_e32 v149, 0.5, v149
	v_add_f32_e32 v150, 1.0, v150
	v_add_f32_e32 v151, 1.0, v151
	v_add_f32_e32 v152, 1.0, v152
	v_add_f32_e32 v153, 1.0, v153
	v_rcp_f32_e32 v150, v150
	v_rcp_f32_e32 v151, v151
	v_rcp_f32_e32 v152, v152
	v_rcp_f32_e32 v153, v153
	v_fmac_f32_e32 v70, v132, v74
	v_fmac_f32_e32 v71, v133, v75
	v_fmac_f32_e32 v72, v134, v76
	v_fmac_f32_e32 v73, v135, v77
	v_fma_f32 v150, v150, -2.0, 1.0
	v_fma_f32 v151, v151, -2.0, 1.0
	v_fma_f32 v152, v152, -2.0, 1.0
	v_fma_f32 v153, v153, -2.0, 1.0
	v_add_f32_e32 v150, 1.0, v150
	v_add_f32_e32 v151, 1.0, v151
	v_add_f32_e32 v152, 1.0, v152
	v_add_f32_e32 v153, 1.0, v153
	v_mul_f32_e32 v146, v146, v150
	v_mul_f32_e32 v147, v147, v151
	v_mul_f32_e32 v148, v148, v152
	v_mul_f32_e32 v149, v149, v153
	v_mul_f32_e32 v146, v70, v146
	v_mul_f32_e32 v147, v71, v147
	v_mul_f32_e32 v148, v72, v148
	v_mul_f32_e32 v149, v73, v149
	v_cvt_pk_bf16_f32 v150, v146, v147
	v_cvt_pk_bf16_f32 v151, v148, v149
	global_store_dwordx2 v130, v[150:151], s[24:25]
	s_add_u32 s24, s24, 0x800
	s_addc_u32 s25, s25, 0
	s_cmp_lg_u32 s18, 0x7f
	s_cbranch_scc1 .Llf_nolast
	s_lshl_b32 s19, s14, 11
	s_add_u32 s28, s94, 0x43be000
	s_addc_u32 s29, s95, 0
	s_add_u32 s28, s28, s19
	s_addc_u32 s29, s29, 0
	global_store_dwordx4 v129, v[70:73], s[28:29]
